# FFN2-down weight conversion moved into the idle tail of the FFN1 converter workgroups; FFN2 gate-up GEMM on all 256 workgroups; M-interval trim
# baseline (speedup 1.0000x reference)
; #define LAS __attribute__((address_space(3)))
;     LAS float* scr = (LAS float*)(F.lds + RING_OFF + F.wave * 16384);
;     const int nblk = nbn ? nbn : N / 32, nall = (K / 64) * nblk, nitems = (int)((long)nall * f1 / 16);
;     int it = (int)((long)nall * f0 / 16) + w0; if (it >= nitems) return;
;     f32x4 va[8], vb[8], vc[8];
;     __builtin_amdgcn_s_waitcnt(0x0F70);
;     const int last = nitems - 1, ntri = ((nitems - it + nw - 1) / nw + 2) / 3;
;     int i1 = min(it + nw, last);
;     p0_item_load(W, N, nblk, nb0, it, F.lane, va);
;     p0_item_load(W, N, nblk, nb0, i1, F.lane, vb); __builtin_amdgcn_sched_barrier(0);
; __global__ void __launch_bounds__(NWAVES * 64, 2) mk_fwd(Args args) {
;     ...
;     if (IN(1)) _Pragma("unroll") for (int rep = 0; rep < NREP(1); ++rep) {
;         if (bx < NG1) {
;         pg8::Gemm g{Hb, (const bf16*)(args.ws + WS_WGU1), M, 2 * DFF, D}; pg8::SampleOrderGated S; S.init(2 * DFF, D, NG1, bx, 1);
;         S.ctr = (const unsigned*)(args.ws + WS_CTL) + CW_GATE; S.nconv = (unsigned)(G - NG1); S.base = S.nconv * (unsigned)((NPN1 - GATE_G0 + GATE_SG - 1) / GATE_SG) * rep; S.g0 = GATE_G0; S.sg = GATE_SG; S.seen = 0;
;         pg8::EpiSwiGLU E{ACT, DFF};
;         pg8::gemm_phase<pg8::EpiSwiGLU, pg8::SampleOrderGated, PG8_ALIGN, PG8_SP2>(F.lds + RING_OFF, g, S, E);
;         } else { convert_beside_ffn1(F, args, (bx - NG1) * NWAVES + F.wave, (G - NG1) * NWAVES); ssm_discretise(F, args, (bx - NG1) * (NWAVES * 64) + F.tid); }
.LBB0_84:
	s_load_dwordx16 s[12:27], s[0:1], 0x40
	s_load_dwordx16 s[48:63], s[0:1], 0x80
	s_add_u32 s0, s96, 0x35400000
	s_addc_u32 s1, s97, 0
	s_mov_b32 s80, s46
	s_waitcnt lgkmcnt(0)
	v_writelane_b32 v236, s12, 20
	s_mov_b32 s6, s64
	s_nop 0
	v_writelane_b32 v236, s13, 21
	v_writelane_b32 v236, s14, 22
	v_writelane_b32 v236, s15, 23
	v_writelane_b32 v236, s16, 24
	v_writelane_b32 v236, s17, 25
	v_writelane_b32 v236, s18, 26
	v_writelane_b32 v236, s19, 27
	v_writelane_b32 v236, s20, 28
	v_writelane_b32 v236, s21, 29
	v_writelane_b32 v236, s22, 30
	v_writelane_b32 v236, s23, 31
	v_writelane_b32 v236, s24, 32
	v_writelane_b32 v236, s25, 33
	v_writelane_b32 v236, s26, 34
	v_writelane_b32 v236, s27, 35
	v_writelane_b32 v236, s0, 36
	s_nop 1
	v_writelane_b32 v236, s1, 37
	s_add_u32 s0, s96, 0x39600000
	s_addc_u32 s1, s97, 0
	v_writelane_b32 v236, s0, 38
	s_cmp_lt_i32 s8, 2
	s_nop 0
	v_writelane_b32 v236, s1, 39
	s_cselect_b64 s[0:1], -1, 0
	v_readlane_b32 s81, v236, 18
	v_writelane_b32 v236, s48, 40
	s_cmp_gt_i32 s9, 1
	s_cselect_b64 s[2:3], -1, 0
	v_writelane_b32 v236, s49, 41
	v_writelane_b32 v236, s50, 42
	v_writelane_b32 v236, s51, 43
	v_writelane_b32 v236, s52, 44
	v_writelane_b32 v236, s53, 45
	v_writelane_b32 v236, s54, 46
	v_writelane_b32 v236, s55, 47
	v_writelane_b32 v236, s56, 48
	v_writelane_b32 v236, s57, 49
	v_writelane_b32 v236, s58, 50
	v_writelane_b32 v236, s59, 51
	v_writelane_b32 v236, s60, 52
	s_and_b64 s[0:1], s[0:1], s[2:3]
	v_writelane_b32 v236, s61, 53
	s_andn2_b64 vcc, exec, s[0:1]
	v_writelane_b32 v236, s62, 54
	v_writelane_b32 v236, s63, 55
	s_cbranch_vccnz .LBB0_224
	s_add_u32 s8, s96, 0xc00000
	s_addc_u32 s9, s97, 0
	s_cmpk_lt_i32 s64, 0xe0
	v_lshlrev_b32_e32 v1, 2, v0
	s_mov_b64 s[0:1], -1
	s_cbranch_scc1 .LBB0_125
	s_mov_b32 s98, 0
	s_add_i32 s16, s64, 0xffffff20
	s_lshl_b32 s0, s16, 3
	s_add_i32 s18, s81, s0
	s_add_i32 s17, s90, 0xfffff900
	s_add_i32 s23, s17, s18
	s_cmpk_lt_i32 s18, 0xc00
	s_mul_hi_i32 s2, s18, 0x2aaaaaab
	s_cselect_b64 s[0:1], -1, 0
	s_lshr_b32 s3, s2, 31
	s_ashr_i32 s2, s2, 3
	s_add_i32 s2, s2, s3
	s_min_i32 s24, s23, 0xbff
	s_mul_i32 s3, s2, 48
	s_sub_i32 s25, s18, s3
	s_mul_hi_i32 s3, s24, 0x2aaaaaab
	s_lshr_b32 s5, s3, 31
	s_ashr_i32 s3, s3, 3
	s_add_i32 s5, s3, s5
	s_mul_i32 s3, s5, 48
	v_lshrrev_b32_e32 v116, 3, v198
	s_sub_i32 s26, s24, s3
	s_lshl_b32 s3, s81, 14
	s_waitcnt vmcnt(14)
	v_lshl_or_b32 v6, s2, 6, v116
	s_mov_b32 s28, 0xac00
	v_mov_b64_e32 v[2:3], s[82:83]
	v_and_b32_e32 v100, 28, v1
	v_lshl_or_b32 v7, s5, 6, v116
	s_add_i32 s10, s3, 0
	v_mad_i64_i32 v[4:5], s[2:3], v6, s28, v[2:3]
	v_mov_b32_e32 v103, 0
	v_lshlrev_b32_e32 v102, 2, v100
	v_mad_i64_i32 v[2:3], s[2:3], v7, s28, v[2:3]
	v_lshl_add_u64 v[106:107], v[2:3], 0, v[102:103]
	v_lshlrev_b32_e32 v2, 3, v0
	v_and_b32_e32 v98, 56, v2
	v_lshlrev_b32_e32 v2, 1, v98
	v_mov_b32_e32 v3, v103
	v_lshl_add_u64 v[104:105], v[4:5], 0, v[102:103]
	v_mul_u32_u24_e32 v4, 0x84, v98
	v_lshl_add_u64 v[108:109], s[8:9], 0, v[2:3]
	v_lshlrev_b32_e32 v2, 2, v116
	v_add3_u32 v122, s10, v4, v2
	v_mov_b64_e32 v[2:3], s[84:85]
	v_mad_i64_i32 v[4:5], s[2:3], v6, s28, v[2:3]
	s_sub_i32 s2, 0x700, s90
	s_max_i32 s20, s17, s2
	v_lshl_add_u64 v[110:111], v[4:5], 0, v[102:103]
	v_cvt_f32_u32_e32 v4, s20
	v_mad_i64_i32 v[2:3], s[2:3], v7, s28, v[2:3]
	v_lshl_add_u64 v[112:113], v[2:3], 0, v[102:103]
	v_rcp_iflag_f32_e32 v2, v4
	s_sub_i32 s19, s90, s18
	s_add_i32 s4, s19, 0x4ff
	s_sub_i32 s3, 0xfffffb01, s19
	v_mul_f32_e32 v2, 0x4f7ffffe, v2
	v_cvt_u32_f32_e32 v2, v2
	s_ashr_i32 s2, s4, 31
	s_max_i32 s3, s4, s3
	s_sub_i32 s4, 0, s20
	v_readfirstlane_b32 s5, v2
	s_mul_i32 s4, s4, s5
	s_mul_hi_u32 s4, s5, s4
	s_add_i32 s22, s5, s4
	s_mul_hi_u32 s4, s3, s22
	s_mul_i32 s5, s4, s20
	s_ashr_i32 s21, s17, 31
	s_sub_i32 s3, s3, s5
	v_add_u32_e32 v117, s10, v102
	s_xor_b32 s2, s2, s21
	s_add_i32 s5, s4, 1
	s_sub_i32 s10, s3, s20
	s_cmp_ge_u32 s3, s20
	s_cselect_b32 s4, s5, s4
	s_cselect_b32 s3, s10, s3
	s_add_i32 s5, s4, 1
	s_cmp_ge_u32 s3, s20
	s_cselect_b32 s3, s5, s4
	s_xor_b32 s3, s3, s2
	s_sub_i32 s4, s3, s2
	s_cmp_gt_i32 s4, 0
	s_cselect_b64 s[2:3], -1, 0
	s_add_i32 s4, s4, 2
	v_cndmask_b32_e64 v2, 0, 1, s[0:1]
	s_mul_hi_u32 s4, s4, 0xaaaaaaab
	v_cmp_ne_u32_e64 s[0:1], 1, v2
	v_cndmask_b32_e64 v2, 0, 1, s[2:3]
	s_mov_b32 s27, 14
	s_mov_b32 s11, 0
	v_mul_u32_u24_e32 v118, 0x84, v116
	v_or_b32_e32 v119, 8, v116
	v_or_b32_e32 v120, 16, v116
	v_or_b32_e32 v121, 24, v116
	s_lshr_b32 s29, s4, 1
	s_mov_b32 s30, 0x56000
	s_mov_b32 s31, 0xac000
	s_mov_b32 s34, 0x102000
	s_mov_b32 s35, 0x158000
	s_mov_b32 s36, 0x1ae000
	s_mov_b32 s37, 0x204000
	s_mov_b32 s38, 0x25a000
	v_cmp_ne_u32_e64 s[4:5], 1, v2
	s_branch .LBB0_88

; __device__ __forceinline__ void p0_item_load(const float* __restrict__ W, int N, int nblk, int nb0, int item, int lane, f32x4 (&v)[8]) {
;     const int kb = item / nblk, nb = nb0 + item % nblk;
;     const float* src = W + (size_t)(64 * kb + (lane >> 3)) * N + 32 * nb + 4 * (lane & 7);
; #pragma unroll
;     for (int i = 0; i < 8; ++i) v[i] = __builtin_nontemporal_load((const f32x4*)(src + (size_t)(8 * i) * N));
; }
;     ...
;     const int last = nitems - 1, ntri = ((nitems - it + nw - 1) / nw + 2) / 3;
;     int i1 = min(it + nw, last);
;     p0_item_load(W, N, nblk, nb0, it, F.lane, va);
;     p0_item_load(W, N, nblk, nb0, i1, F.lane, vb); __builtin_amdgcn_sched_barrier(0);
.LBB0_98:
	s_ashr_i32 s0, s18, 31
	s_lshr_b32 s0, s0, 25
	s_add_i32 s0, s18, s0
	s_ashr_i32 s2, s0, 7
	s_and_b32 s0, s0, 0x7ffff80
	s_sub_i32 s0, s18, s0
	s_lshl_b32 s0, s0, 5
	s_waitcnt vmcnt(15)
	v_lshl_or_b32 v2, s2, 6, v116
	s_ashr_i32 s1, s0, 31
	v_ashrrev_i32_e32 v3, 31, v2
	s_cmpk_gt_i32 s18, 0x55ff
	v_lshlrev_b64 v[102:103], 14, v[2:3]
	v_lshlrev_b32_e32 v100, 2, v100
	s_cbranch_scc1 .LBB0_102
	s_min_i32 s5, s23, 0x55ff
	s_ashr_i32 s2, s5, 31
	s_lshr_b32 s2, s2, 25
	v_lshl_add_u64 v[2:3], s[86:87], 0, v[102:103]
	s_add_i32 s2, s5, s2
	v_lshl_add_u64 v[2:3], s[0:1], 2, v[2:3]
	v_mov_b32_e32 v101, 0
	s_ashr_i32 s3, s2, 7
	s_waitcnt vmcnt(8)
	v_lshl_add_u64 v[18:19], v[2:3], 0, v[100:101]
	s_and_b32 s2, s2, 0x7ffff80
	v_lshl_or_b32 v2, s3, 6, v116
	s_sub_i32 s2, s5, s2
	v_ashrrev_i32_e32 v3, 31, v2
	v_lshlrev_b64 v[2:3], 14, v[2:3]
	s_lshl_b32 s2, s2, 5
	v_lshl_add_u64 v[2:3], s[86:87], 0, v[2:3]
	s_ashr_i32 s3, s2, 31
	v_lshl_add_u64 v[2:3], s[2:3], 2, v[2:3]
	s_mov_b32 s10, 0x20000
	s_waitcnt vmcnt(1)
	v_lshl_add_u64 v[58:59], v[2:3], 0, v[100:101]
	v_add_co_u32_e32 v2, vcc, s10, v18
	s_mov_b32 s11, 0x40000
	s_nop 0
	v_addc_co_u32_e32 v3, vcc, 0, v19, vcc
	v_add_co_u32_e32 v6, vcc, s11, v18
	s_mov_b32 s12, 0x60000
	s_nop 0
	v_addc_co_u32_e32 v7, vcc, 0, v19, vcc
	v_add_co_u32_e32 v10, vcc, s12, v18
	s_mov_b32 s13, 0x80000
	s_nop 0
	v_addc_co_u32_e32 v11, vcc, 0, v19, vcc
	v_add_co_u32_e32 v14, vcc, s13, v18
	s_mov_b32 s14, 0xa0000
	s_nop 0
	v_addc_co_u32_e32 v15, vcc, 0, v19, vcc
	v_add_co_u32_e32 v20, vcc, s14, v18
	s_mov_b32 s15, 0xc0000
	s_nop 0
	v_addc_co_u32_e32 v21, vcc, 0, v19, vcc
	v_add_co_u32_e32 v26, vcc, s15, v18
	s_mov_b32 s24, 0xe0000
	s_nop 0
	v_addc_co_u32_e32 v27, vcc, 0, v19, vcc
	s_waitcnt vmcnt(0)
	global_load_dwordx4 v[2:5], v[2:3], off nt
	s_nop 0
	global_load_dwordx4 v[6:9], v[6:7], off nt
	s_nop 0
	global_load_dwordx4 v[10:13], v[10:11], off nt
	s_nop 0
	global_load_dwordx4 v[14:17], v[14:15], off nt
	s_nop 0
	global_load_dwordx4 v[22:25], v[20:21], off nt
	global_load_dwordx4 v[34:37], v[26:27], off nt
	v_add_co_u32_e32 v26, vcc, s24, v18
	s_add_i32 s2, s19, 0x4eff
	s_nop 0
	v_addc_co_u32_e32 v27, vcc, 0, v19, vcc
	v_add_co_u32_e32 v28, vcc, s10, v58
	global_load_dwordx4 v[30:33], v[18:19], off nt
	s_nop 0
	global_load_dwordx4 v[18:21], v[58:59], off nt
	v_addc_co_u32_e32 v29, vcc, 0, v59, vcc
	v_add_co_u32_e32 v38, vcc, s11, v58
	global_load_dwordx4 v[42:45], v[26:27], off nt
	s_nop 0
	global_load_dwordx4 v[26:29], v[28:29], off nt
	v_addc_co_u32_e32 v39, vcc, 0, v59, vcc
	v_add_co_u32_e32 v46, vcc, s12, v58
	s_sub_i32 s4, 0xffffb101, s19
	s_nop 0
	v_addc_co_u32_e32 v47, vcc, 0, v59, vcc
	v_add_co_u32_e32 v50, vcc, s13, v58
	global_load_dwordx4 v[38:41], v[38:39], off nt
	s_nop 0
	global_load_dwordx4 v[46:49], v[46:47], off nt
	v_addc_co_u32_e32 v51, vcc, 0, v59, vcc
	v_add_co_u32_e32 v54, vcc, s14, v58
	s_ashr_i32 s3, s2, 31
	s_nop 0
	v_addc_co_u32_e32 v55, vcc, 0, v59, vcc
	v_add_co_u32_e32 v60, vcc, 0xc0000, v58
	global_load_dwordx4 v[50:53], v[50:51], off nt
	s_nop 0
	global_load_dwordx4 v[54:57], v[54:55], off nt
	v_addc_co_u32_e32 v61, vcc, 0, v59, vcc
	v_add_co_u32_e32 v62, vcc, 0xe0000, v58
	s_max_i32 s2, s2, s4
	s_nop 0
	v_addc_co_u32_e32 v63, vcc, 0, v59, vcc
	global_load_dwordx4 v[58:61], v[60:61], off nt
	s_nop 0
	global_load_dwordx4 v[62:65], v[62:63], off nt
	s_mul_hi_u32 s4, s2, s22
	s_mul_i32 s25, s4, s20
	s_sub_i32 s2, s2, s25
	s_xor_b32 s3, s3, s21
	s_add_i32 s25, s4, 1
	s_sub_i32 s26, s2, s20
	s_cmp_ge_u32 s2, s20
	s_cselect_b32 s4, s25, s4
	s_cselect_b32 s2, s26, s2
	s_add_i32 s25, s4, 1
	s_cmp_ge_u32 s2, s20
	s_cselect_b32 s2, s25, s4
	s_xor_b32 s2, s2, s3
	s_sub_i32 s2, s2, s3
	s_cmp_lt_i32 s2, 1
	s_cbranch_scc1 .LBB0_102
	v_lshlrev_b32_e32 v66, 1, v98
	v_mov_b32_e32 v67, v101
	s_add_i32 s2, s2, 2
	v_lshl_add_u64 v[66:67], s[96:97], 0, v[66:67]
	s_mov_b64 s[26:27], 0xb800000
	s_cmp_eq_u32 s98, 1
	s_cselect_b32 s26, 0x27a00000, s26
	s_mul_hi_u32 s2, s2, 0xaaaaaaab
	v_lshl_add_u64 v[104:105], v[66:67], 0, s[26:27]
	s_lshr_b32 s25, s2, 1
	s_movk_i32 s26, 0x5600
	s_mov_b32 s28, s18

; #define LAS __attribute__((address_space(3)))
;     LAS float* scr = (LAS float*)(F.lds + RING_OFF + F.wave * 16384);
;     const int nblk = nbn ? nbn : N / 32, nall = (K / 64) * nblk, nitems = (int)((long)nall * f1 / 16);
;     int it = (int)((long)nall * f0 / 16) + w0; if (it >= nitems) return;
; __device__ __forceinline__ void convert_beside_ffn1(Frame& F, const Args& A, int w0, int nw) {
;     ...
;     p0_transpose(F, A.in[7], DFF, D, (bf16*)(F.ws + WS_WD1), 0, w0, nw);
;     p0_transpose(F, A.in[9], D, INW, (bf16*)(F.ws + WS_WIN), 0, w0, nw);
;     p0_transpose(F, A.in[22], GW, D, (bf16*)(F.ws + WS_WGOUT), 0, w0, nw);
; }
; __device__ __forceinline__ void convert_beside_ffn2(Frame& F, const Args& A, int w0, int nw) {
;     p0_transpose(F, A.in[27], DFF, D, (bf16*)(F.ws + WS_WD2), 0, w0, nw);
.LBB0_102:
	s_cmp_eq_u32 s98, 1
	s_cbranch_scc1 .Lwd2_done
	s_mov_b32 s98, 1
	v_readlane_b32 s86, v236, 9
	v_readlane_b32 s87, v236, 10
	v_lshrrev_b32_e32 v100, 2, v100
	s_branch .LBB0_98

; #define GRID_BAR() do { if (!MK_SPLIT) xcd_barrier(bar); } while (0)
; #define BOTH(k) (IN(k) && IN((k) + 1))
; __device__ __forceinline__ void p0_item_load(const float* __restrict__ W, int N, int nblk, int nb0, int item, int lane, f32x4 (&v)[8]) {
;     const int kb = item / nblk, nb = nb0 + item % nblk;
;     const float* src = W + (size_t)(64 * kb + (lane >> 3)) * N + 32 * nb + 4 * (lane & 7);
; #pragma unroll
;     for (int i = 0; i < 8; ++i) v[i] = __builtin_nontemporal_load((const f32x4*)(src + (size_t)(8 * i) * N));
; }
; __global__ void __launch_bounds__(NWAVES * 64, 2) mk_fwd(Args args) {
;     ...
;     if (IN(11)) _Pragma("unroll") for (int rep = 0; rep < NREP(11); ++rep) {
;         if (bx < NG11) {
;         pg8::Gemm g{Hb, (const bf16*)(args.ws + WS_WGU2), M, 2 * DFF, D}; pg8::SampleOrder S; S.init(2 * DFF, D, NG11, bx, 1);
;         pg8::EpiSwiGLU E{ACT, DFF};
;         pg8::gemm_phase<pg8::EpiSwiGLU, pg8::SampleOrder, PG8_ALIGN, PG8_SP2>(F.lds + RING_OFF, g, S, E);
;         } else convert_beside_ffn2(F, args, (bx - NG11) * NWAVES + F.wave, (G - NG11) * NWAVES);
;         if (BOTH(11)) GRID_BAR();
;     }
.LBB0_1297:
	s_cmp_lt_i32 s8, 12
	s_cselect_b64 s[0:1], -1, 0
	s_cmp_gt_i32 s9, 11
	s_cselect_b64 s[2:3], -1, 0
	s_and_b64 s[0:1], s[0:1], s[2:3]
	s_andn2_b64 vcc, exec, s[0:1]
	s_cbranch_vccnz .LBB0_1391
	s_cmpk_gt_i32 s64, 0x7fff
	v_lshlrev_b32_e32 v1, 2, v0
	s_mov_b64 s[0:1], -1
	s_cbranch_scc0 .LBB0_1304
	s_add_i32 s17, s88, 0xfffff880
	s_cmpk_gt_i32 s17, 0x55ff
	s_cbranch_scc1 .LBB0_1303
	s_add_i32 s4, s90, 0xfffff880
	s_add_i32 s0, s4, s17
	s_min_i32 s3, s0, 0x55ff
	s_ashr_i32 s0, s17, 31
	s_lshr_b32 s0, s0, 25
	s_add_i32 s0, s17, s0
	s_ashr_i32 s1, s0, 7
	v_lshrrev_b32_e32 v102, 3, v198
	s_and_b32 s0, s0, 0x7ffff80
	s_waitcnt vmcnt(0)
	v_lshl_or_b32 v2, s1, 6, v102
	v_readlane_b32 s8, v236, 3
	s_sub_i32 s0, s17, s0
	s_waitcnt lgkmcnt(0)
	v_ashrrev_i32_e32 v3, 31, v2
	v_readlane_b32 s14, v236, 9
	v_readlane_b32 s15, v236, 10
	v_lshlrev_b64 v[2:3], 14, v[2:3]
	s_mov_b64 s[6:7], s[14:15]
	s_lshl_b32 s0, s0, 5
	v_lshl_add_u64 v[2:3], s[6:7], 0, v[2:3]
	s_ashr_i32 s1, s0, 31
	v_and_b32_e32 v66, 28, v1
	v_lshl_add_u64 v[2:3], s[0:1], 2, v[2:3]
	v_mov_b32_e32 v99, 0
	v_lshlrev_b32_e32 v98, 2, v66
	v_lshl_add_u64 v[26:27], v[2:3], 0, v[98:99]
	s_ashr_i32 s0, s3, 31
	s_mov_b32 s5, 0x20000
	s_lshr_b32 s0, s0, 25
	v_add_co_u32_e32 v10, vcc, s5, v26
	s_add_i32 s0, s3, s0
	s_nop 0
	v_addc_co_u32_e32 v11, vcc, 0, v27, vcc
	s_mov_b32 s8, 0x40000
	v_readlane_b32 s9, v236, 4
	s_ashr_i32 s1, s0, 7
	v_add_co_u32_e32 v12, vcc, s8, v26
	s_and_b32 s0, s0, 0x7ffff80
	v_lshl_or_b32 v2, s1, 6, v102
	v_addc_co_u32_e32 v13, vcc, 0, v27, vcc
	s_mov_b32 s9, 0x60000
	v_readlane_b32 s10, v236, 5
	s_sub_i32 s0, s3, s0
	v_ashrrev_i32_e32 v3, 31, v2
	v_add_co_u32_e32 v18, vcc, s9, v26
	v_lshlrev_b64 v[2:3], 14, v[2:3]
	s_lshl_b32 s0, s0, 5
	v_addc_co_u32_e32 v19, vcc, 0, v27, vcc
	s_mov_b32 s10, 0x80000
	v_readlane_b32 s11, v236, 6
	v_lshl_add_u64 v[2:3], s[6:7], 0, v[2:3]
	s_ashr_i32 s1, s0, 31
	v_add_co_u32_e32 v20, vcc, s10, v26
	v_lshl_add_u64 v[2:3], s[0:1], 2, v[2:3]
	s_nop 0
	v_addc_co_u32_e32 v21, vcc, 0, v27, vcc
	s_mov_b32 s11, 0xa0000
	v_readlane_b32 s12, v236, 7
	v_lshl_add_u64 v[58:59], v[2:3], 0, v[98:99]
	s_waitcnt vmcnt(0)
	global_load_dwordx4 v[2:5], v[10:11], off nt
	global_load_dwordx4 v[6:9], v[12:13], off nt
	s_nop 0
	global_load_dwordx4 v[10:13], v[18:19], off nt
	global_load_dwordx4 v[14:17], v[20:21], off nt
	v_add_co_u32_e32 v18, vcc, s11, v26
	s_mov_b32 s12, 0xc0000
	s_nop 0
	v_addc_co_u32_e32 v19, vcc, 0, v27, vcc
	v_readlane_b32 s13, v236, 8
	v_add_co_u32_e32 v20, vcc, s12, v26
	s_mov_b32 s13, 0xe0000
	s_nop 0
	v_addc_co_u32_e32 v21, vcc, 0, v27, vcc
	v_add_co_u32_e32 v38, vcc, s13, v26
	global_load_dwordx4 v[22:25], v[18:19], off nt
	global_load_dwordx4 v[34:37], v[20:21], off nt
	v_addc_co_u32_e32 v39, vcc, 0, v27, vcc
	v_add_co_u32_e32 v40, vcc, s5, v58
	global_load_dwordx4 v[30:33], v[26:27], off nt
	global_load_dwordx4 v[18:21], v[58:59], off nt
	v_addc_co_u32_e32 v41, vcc, 0, v59, vcc
	v_add_co_u32_e32 v50, vcc, s8, v58
	global_load_dwordx4 v[42:45], v[38:39], off nt
	global_load_dwordx4 v[26:29], v[40:41], off nt
	v_addc_co_u32_e32 v51, vcc, 0, v59, vcc
	v_add_co_u32_e32 v52, vcc, s9, v58
	s_sub_i32 s0, 0x780, s90
	s_nop 0
	v_addc_co_u32_e32 v53, vcc, 0, v59, vcc
	v_add_co_u32_e32 v60, vcc, s10, v58
	global_load_dwordx4 v[38:41], v[50:51], off nt
	global_load_dwordx4 v[46:49], v[52:53], off nt
	v_addc_co_u32_e32 v61, vcc, 0, v59, vcc
	v_add_co_u32_e32 v62, vcc, s11, v58
	s_max_i32 s0, s4, s0
	s_nop 0
	v_addc_co_u32_e32 v63, vcc, 0, v59, vcc
	v_add_co_u32_e32 v68, vcc, 0xc0000, v58
	global_load_dwordx4 v[50:53], v[60:61], off nt
	global_load_dwordx4 v[54:57], v[62:63], off nt
	v_addc_co_u32_e32 v69, vcc, 0, v59, vcc
	v_add_co_u32_e32 v70, vcc, 0xe0000, v58
	v_cvt_f32_u32_e32 v67, s0
	s_nop 0
	v_addc_co_u32_e32 v71, vcc, 0, v59, vcc
	global_load_dwordx4 v[58:61], v[68:69], off nt
	global_load_dwordx4 v[62:65], v[70:71], off nt
	v_rcp_iflag_f32_e32 v67, v67
	s_sub_i32 s1, s90, s88
	s_add_i32 s2, s1, 0x55ff
	s_sub_i32 s1, 0xffffaa01, s1
	v_mul_f32_e32 v67, 0x4f7ffffe, v67
	v_cvt_u32_f32_e32 v67, v67
	s_xor_b32 s14, s2, s4
	s_max_i32 s1, s2, s1
	s_sub_i32 s2, 0, s0
	v_readfirstlane_b32 s15, v67
	s_mul_i32 s2, s2, s15
	s_mul_hi_u32 s2, s15, s2
	s_add_i32 s15, s15, s2
	s_mul_hi_u32 s2, s1, s15
	s_mul_i32 s15, s2, s0
	s_sub_i32 s1, s1, s15
	s_ashr_i32 s14, s14, 31
	s_add_i32 s15, s2, 1
	s_sub_i32 s16, s1, s0
	s_cmp_ge_u32 s1, s0
	s_cselect_b32 s2, s15, s2
	s_cselect_b32 s1, s16, s1
	s_add_i32 s15, s2, 1
	s_cmp_ge_u32 s1, s0
	s_cselect_b32 s0, s15, s2
	s_xor_b32 s0, s0, s14
	s_sub_i32 s0, s0, s14
	s_cmp_lt_i32 s0, 1
	s_cbranch_scc1 .LBB0_1303
	s_lshl_b32 s1, s81, 14
	s_add_i32 s1, s1, 0
	v_lshl_add_u32 v68, v66, 2, s1
	v_lshlrev_b32_e32 v66, 3, v0
	v_and_b32_e32 v66, 56, v66
	v_mul_u32_u24_e32 v70, 0x84, v66
	v_lshlrev_b32_e32 v66, 1, v66
	v_mov_b32_e32 v67, v99
	v_lshl_add_u64 v[66:67], s[96:97], 0, v[66:67]
	s_mov_b64 s[14:15], 0x27a00000
	s_add_i32 s0, s0, 2
	v_readlane_b32 s20, v236, 3
	v_mul_u32_u24_e32 v69, 0x84, v102
	v_lshl_add_u64 v[100:101], v[66:67], 0, s[14:15]
	v_lshlrev_b32_e32 v66, 2, v102
	s_mul_hi_u32 s0, s0, 0xaaaaaaab
	v_readlane_b32 s26, v236, 9
	v_readlane_b32 s27, v236, 10
	v_or_b32_e32 v103, 8, v102
	v_or_b32_e32 v104, 16, v102
	v_or_b32_e32 v105, 24, v102
	v_add3_u32 v106, s1, v70, v66
	s_lshr_b32 s14, s0, 1
	v_add_u32_e32 v107, v68, v69
	s_movk_i32 s15, 0x5600
	s_mov_b64 s[6:7], s[26:27]
	v_readlane_b32 s21, v236, 4
	v_readlane_b32 s22, v236, 5
	v_readlane_b32 s23, v236, 6
	v_readlane_b32 s24, v236, 7
	v_readlane_b32 s25, v236, 8

;     __device__ void init(int N, int K, int G, int c, int nsplit_) {
;         base.init(32 * BM, N, G, c); nN = N / BM; nsplit = nsplit_; nkt = K / BK; nsamp = nN * nsplit;
;         const int nfull = 32 * nN, R = nfull % G; fullcnt = nfull / G + (c < R ? 1 : 0);
;         if (R > 0) { sbase = c - R; sstride = G - R; } else { sbase = c; sstride = G; }
;     }
; template <class Epi, class Sched, bool ALIGN_EPI = false, bool SP2 = true>
; __device__ __forceinline__ void gemm_phase(PG8_LAS unsigned char* lds, const Gemm g, const Sched& S, const Epi& E) {
;     ...
;     const int tid = threadIdx.x, wid = __builtin_amdgcn_readfirstlane(tid >> 6), lane = tid & 63, wr = wid >> 2, wc = wid & 3, fr = lane & 15, fq = lane >> 4;
;     const int K = g.K;
;     unsigned voffA[2], voffB[2];
; #pragma unroll
;     for (int i = 0; i < 2; ++i) { int R, C; stage_rc(tid * 16 + i * 8192, R, C); const int Rb = Epi::PERM ? ((R & ~31) + perm32(R & 31)) : R;
;         voffA[i] = (unsigned)(R * K + C) * 2u; voffB[i] = (unsigned)(Rb * K + C) * 2u; }
;     const size_t kstep = (size_t)(BK * 2);
;     const size_t hstep = (size_t)HALF * K * 2;
;     const size_t tstep = 2 * hstep;
;     const unsigned ldsw = (unsigned)wid * 1024u;
;     const int aoff = lds_byte(wr * 64 + fr, fq * 8), boff = lds_byte(wc * 32 + fr, fq * 8);
.LBB0_1307:
	s_lshl_b32 s10, s10, 5
	s_and_b32 s18, s10, 0x60
	s_lshl_b32 s3, s12, 13
	s_lshl_b32 s13, s18, 7
	s_cmpk_gt_i32 s64, 0xbf
	s_cselect_b64 s[14:15], -1, 0
	s_cmpk_lt_i32 s64, 0xc0
	s_cselect_b32 s47, 11, 10
	s_add_i32 s48, s39, 0x18000
	s_mov_b64 s[10:11], 0x80
	v_lshl_add_u64 v[10:11], v[10:11], 0, s[10:11]
	s_mov_b32 m0, s48
	s_add_i32 s49, s39, 0x1a000
	s_waitcnt vmcnt(2)
	s_barrier
	global_load_lds_dwordx4 v[10:11], off
	v_lshl_add_u64 v[8:9], v[8:9], 0, s[10:11]
	s_mov_b32 m0, s49
	s_add_i32 s50, s39, 0x8000
	s_add_i32 s51, s39, 0xa000
	global_load_lds_dwordx4 v[8:9], off
	v_lshl_add_u64 v[4:5], v[4:5], 0, s[10:11]
	s_mov_b32 m0, s50
	s_add_u32 s16, s30, 0x100080
	global_load_lds_dwordx4 v[4:5], off
	v_lshl_add_u64 v[4:5], v[6:7], 0, s[10:11]
	s_mov_b32 m0, s51
	s_addc_u32 s17, s31, 0
	s_add_i32 s52, s39, 0x1c000
	global_load_lds_dwordx4 v[4:5], off
	v_lshl_add_u64 v[4:5], s[16:17], 0, v[202:203]
	s_mov_b32 m0, s52
	s_add_i32 s53, s39, 0x1e000
	global_load_lds_dwordx4 v[4:5], off
	v_lshl_add_u64 v[4:5], s[16:17], 0, v[206:207]
	s_mov_b32 m0, s53
	s_movk_i32 s16, 0x3c0
	global_load_lds_dwordx4 v[4:5], off
	v_lshlrev_b32_e32 v4, 1, v14
	v_lshlrev_b32_e32 v5, 6, v0
	v_and_b32_e32 v7, 15, v0
	v_and_or_b32 v5, v5, s16, v4
	v_and_b32_e32 v6, 32, v1
	v_lshl_or_b32 v4, v7, 6, v4
	v_bitop3_b32 v4, v4, s3, v6 bitop3:0xde
	v_bitop3_b32 v5, s13, v5, v6 bitop3:0xf6
	v_lshlrev_b32_e32 v6, 10, v0
	v_lshl_or_b32 v1, s12, 6, v7
	v_and_b32_e32 v6, 0x60000, v6
	v_lshlrev_b32_e32 v7, 13, v13
	v_or3_b32 v6, v3, v6, v7
	v_add_u32_e32 v208, v6, v12
	v_lshlrev_b32_e32 v6, 6, v15
	v_and_b32_e32 v6, 0xe0000, v6
	s_waitcnt vmcnt(6)
	v_or3_b32 v3, v3, v6, v7
	s_cmpk_lt_u32 s1, 0x100
	v_add_u32_e32 v210, v3, v12
	v_cndmask_b32_e64 v3, 0, 1, s[14:15]
	v_add_u32_e32 v220, 0, v5
	s_sext_i32_i16 s3, s0
	s_cselect_b64 s[12:13], -1, 0
	s_add_i32 s54, s64, 0xfffffd00
	v_or_b32_e32 v199, s18, v14
	v_mov_b32_e32 v209, v2
	v_mov_b32_e32 v211, v2
	v_cmp_ne_u32_e64 s[0:1], 1, v3
	v_add_u32_e32 v221, 0x10000, v220
	v_add_u32_e32 v222, 0x14000, v220
	v_add_u32_e32 v223, 0, v4
	s_movk_i32 s55, 0x5600
	v_mov_b64_e32 v[212:213], 0xabf
	s_mov_b32 s19, 0
	s_barrier
	s_branch .LBB0_1310

;     __device__ bool next(int i, Unit& u) const {
;         if (i < fullcnt) { base.next(i, u); u.kt0 = 0; u.nkt = nkt; u.flags = 0; return true; }
;         if (sbase < 0) return false;
;         const int s = sbase + (i - fullcnt) * sstride; if (s >= nsamp) return false;
;         const int ks = s / nN, pairs = nkt >> 1, q = pairs / nsplit, r = pairs % nsplit;
;         u.pm = 32; u.pn = s % nN; u.kt0 = 2 * (ks * q + (ks < r ? ks : r)); u.nkt = 2 * (q + (ks < r ? 1 : 0)); u.flags = 1 | (nsplit > 1 ? 2 : 0) | (ks << 8); return true;
.LBB0_1310:
	s_add_i32 s56, s19, 1
	s_cmp_ge_u32 s56, s47
	s_mov_b64 s[22:23], -1
	s_cbranch_scc0 .LBB0_1315
	s_and_b64 vcc, exec, s[0:1]
	s_mov_b64 s[22:23], 0
	s_cbranch_vccnz .LBB0_1314
	s_lshl_b32 s19, s19, 6
	s_add_i32 s19, s19, s54
	s_mov_b64 s[20:21], 0
	s_cmpk_gt_i32 s19, 0x55
	s_mov_b32 s17, s14
	s_mov_b32 s15, s16
	s_cbranch_scc1 .LBB0_1315
	s_mul_hi_i32 s15, s19, 0x2fa0be83
	s_lshr_b32 s17, s15, 31
	s_ashr_i32 s15, s15, 4
	s_add_i32 s17, s15, s17
	s_mul_i32 s15, s17, 0x56
	s_sub_i32 s15, s19, s15
	s_mul_i32 s18, s17, 0x42
	s_mov_b32 s57, 1
	s_mov_b32 s17, 32
	s_mov_b64 s[20:21], -1
	s_branch .LBB0_1315

;     __host__ __device__ bool next(int i, Unit& u) const {
;         const long L = (long)i * G + c; if (L >= nwg) return false;
;         int wgid = (int)L; { const int q = nwg / NXCD, r = nwg % NXCD, xcd = wgid % NXCD, off = wgid / NXCD; wgid = (xcd < r ? xcd * (q + 1) : r * (q + 1) + (xcd - r) * q) + off; }
;         const int nig = WGM * nN, gid = wgid / nig, fm = gid * WGM, gsz = (nM - fm) < WGM ? (nM - fm) : WGM;
;         u.pm = fm + ((wgid % nig) % gsz); u.pn = (wgid % nig) / gsz; return true;
.LBB0_1315:
	s_andn2_b64 vcc, exec, s[22:23]
	s_cbranch_vccnz .LBB0_1319
	s_mul_i32 s17, s56, 0x100
	s_mul_hi_u32 s15, s56, 0x100
	s_add_u32 s18, s17, s64
	s_addc_u32 s19, s15, s37
	v_cmp_gt_i64_e32 vcc, s[18:19], v[212:213]
	s_cbranch_vccnz .LBB0_1318
	s_ashr_i32 s14, s18, 31
	s_lshr_b32 s14, s14, 29
	s_add_i32 s14, s18, s14
	s_ashr_i32 s15, s14, 3
	s_and_b32 s14, s14, -8
	s_sub_i32 s14, s18, s14
	s_cmp_lt_i32 s14, 0
	s_cselect_b32 s16, s38, 0x158
	s_mul_i32 s14, s14, s16
	s_add_i32 s14, s14, s15
	s_mul_hi_i32 s15, s14, 0x2fa0be83
	s_lshr_b32 s16, s15, 31
	s_ashr_i32 s15, s15, 6
	s_add_i32 s15, s15, s16
	s_lshl_b32 s16, s15, 2
	s_mulk_i32 s15, 0x158
	s_sub_i32 s14, s14, s15
	s_bfe_u32 s15, s14, 0x2001d
	s_add_i32 s15, s14, s15
	s_sext_i32_i16 s17, s15
	s_and_b32 s15, s15, 0xfffc
	s_sub_i32 s14, s14, s15
	s_sext_i32_i16 s14, s14
	s_add_i32 s14, s16, s14
	s_ashr_i32 s16, s17, 2

; __global__ void __launch_bounds__(NWAVES * 64, 2) mk_fwd(Args args) {
	.amdhsa_kernel _Z6mk_fwd4Args
		.amdhsa_group_segment_fixed_size 0
		.amdhsa_private_segment_fixed_size 0
		.amdhsa_kernarg_size 512
		.amdhsa_user_sgpr_count 2
		.amdhsa_user_sgpr_dispatch_ptr 0
		.amdhsa_user_sgpr_queue_ptr 0
		.amdhsa_user_sgpr_kernarg_segment_ptr 1
		.amdhsa_user_sgpr_dispatch_id 0
		.amdhsa_user_sgpr_kernarg_preload_length 0
		.amdhsa_user_sgpr_kernarg_preload_offset 0
		.amdhsa_user_sgpr_private_segment_size 0
		.amdhsa_uses_dynamic_stack 0
		.amdhsa_enable_private_segment 0
		.amdhsa_system_sgpr_workgroup_id_x 1
		.amdhsa_system_sgpr_workgroup_id_y 0
		.amdhsa_system_sgpr_workgroup_id_z 0
		.amdhsa_system_sgpr_workgroup_info 0
		.amdhsa_system_vgpr_workitem_id 0
		.amdhsa_next_free_vgpr 237
		.amdhsa_next_free_sgpr 100
		.amdhsa_accum_offset 240
		.amdhsa_reserve_vcc 1
		.amdhsa_float_round_mode_32 0
		.amdhsa_float_round_mode_16_64 0
		.amdhsa_float_denorm_mode_32 3
		.amdhsa_float_denorm_mode_16_64 3
		.amdhsa_dx10_clamp 1
		.amdhsa_ieee_mode 1
		.amdhsa_fp16_overflow 0
		.amdhsa_tg_split 0
		.amdhsa_exception_fp_ieee_invalid_op 0
		.amdhsa_exception_fp_denorm_src 0
		.amdhsa_exception_fp_ieee_div_zero 0
		.amdhsa_exception_fp_ieee_overflow 0
		.amdhsa_exception_fp_ieee_underflow 0
		.amdhsa_exception_fp_ieee_inexact 0
		.amdhsa_exception_int_div_zero 0
	.end_amdhsa_kernel
